# attention outputs stored 16 B per lane (row exchange via ds_bpermute); scan consumer hand-written, y moved to yraw by the idle waves
# speedup vs baseline: 1.0066x; 1.0016x over previous
.LBB0_1116:
	s_or_b64 exec, exec, s[10:11]
	s_lshl_b32 s22, s2, 9
	s_cmp_gt_i32 s2, 63
	s_waitcnt lgkmcnt(0)
	s_barrier
	s_cbranch_scc1 .LBB0_1130
	v_readfirstlane_b32 s12, v141
	s_and_b32 s10, s12, 0xffffff80
	s_cmpk_lg_i32 s10, 0x100
	s_mov_b64 s[10:11], -1
	s_cbranch_scc0 .Lsc_helper
	s_cmpk_lt_u32 s12, 0x80
	s_cbranch_scc0 .LBB0_1122
	s_lshr_b32 s13, s12, 6
	v_and_b32_e32 v238, 63, v141
	v_lshlrev_b32_e32 v232, 4, v238
	v_lshlrev_b32_e32 v233, 3, v238
	s_lshl_b32 s10, s13, 10
	s_add_i32 s10, s10, 0x2800
	v_add_u32_e32 v233, s10, v233
	v_add_u32_e32 v234, 0x200, v233
	v_lshrrev_b32_e32 v239, 4, v238
	v_lshlrev_b32_e32 v235, 4, v239
	v_add_u32_e32 v235, 0x3000, v235
	v_and_b32_e32 v241, 15, v238
	v_lshlrev_b32_e32 v236, 6, v241
	v_lshl_add_u32 v236, v239, 3, v236
	s_lshl_b32 s10, s13, 11
	s_add_i32 s10, s10, 0x23c00
	v_add_u32_e32 v236, s10, v236
	v_mov_b32_e32 v0, 0
	v_mov_b32_e32 v1, 0
	v_mov_b32_e32 v2, 0
	v_mov_b32_e32 v3, 0
	v_mov_b32_e32 v4, 0
	v_mov_b32_e32 v5, 0
	v_mov_b32_e32 v6, 0
	v_mov_b32_e32 v7, 0
	v_mov_b32_e32 v8, 0
	v_mov_b32_e32 v9, 0
	v_mov_b32_e32 v10, 0
	v_mov_b32_e32 v11, 0
	v_mov_b32_e32 v12, 0
	v_mov_b32_e32 v13, 0
	v_mov_b32_e32 v14, 0
	v_mov_b32_e32 v15, 0
	v_mov_b32_e32 v16, 0
	v_mov_b32_e32 v17, 0
	v_mov_b32_e32 v18, 0
	v_mov_b32_e32 v19, 0
	v_mov_b32_e32 v20, 0
	v_mov_b32_e32 v21, 0
	v_mov_b32_e32 v22, 0
	v_mov_b32_e32 v23, 0
	v_mov_b32_e32 v24, 0
	v_mov_b32_e32 v25, 0
	v_mov_b32_e32 v26, 0
	v_mov_b32_e32 v27, 0
	v_mov_b32_e32 v28, 0
	v_mov_b32_e32 v29, 0
	v_mov_b32_e32 v30, 0
	v_mov_b32_e32 v31, 0
	v_mov_b32_e32 v122, 0
	v_mov_b32_e32 v123, 0
	v_mov_b32_e32 v126, 0
	v_mov_b32_e32 v127, 0
	v_mov_b32_e32 v218, 0
	v_mov_b32_e32 v219, 0
	v_mov_b32_e32 v222, 0
	v_mov_b32_e32 v223, 0
	s_mov_b32 s17, 0
	s_mov_b32 s18, 0
	s_mov_b32 s16, 0
	s_waitcnt vmcnt(0) lgkmcnt(0)
	s_barrier
	v_add_u32_e32 v238, s18, v232
	v_add_u32_e32 v239, s18, v233
	v_add_u32_e32 v240, s18, v234
	ds_read_b128 v[80:83], v238
	ds_read_b128 v[84:87], v238 offset:1024
	ds_read_b128 v[88:91], v238 offset:2048
	ds_read_b128 v[92:95], v238 offset:3072
	ds_read_b128 v[96:99], v238 offset:4096
	ds_read_b128 v[100:103], v238 offset:5120
	ds_read_b128 v[104:107], v238 offset:6144
	ds_read_b128 v[108:111], v238 offset:7168
	ds_read_b128 v[112:115], v238 offset:8192
	ds_read_b128 v[116:119], v238 offset:9216
	ds_read_b64 v[120:121], v239
	ds_read_b64 v[134:135], v239
	ds_read_b64 v[124:125], v240
	ds_read_b64 v[146:147], v240
	v_add_u32_e32 v241, s18, v235
	ds_read_b128 v[64:67], v241
	ds_read_b128 v[68:71], v241 offset:64
	ds_read_b128 v[72:75], v241 offset:128
	ds_read_b128 v[76:79], v241 offset:192
	s_mov_b32 s17, 1
	s_movk_i32 s18, 0x3400
	s_waitcnt lgkmcnt(0)
.Lsc_loop:
	v_add_u32_e32 v238, s18, v232
	v_add_u32_e32 v239, s18, v233
	v_add_u32_e32 v240, s18, v234
	ds_read_b128 v[176:179], v238
	ds_read_b128 v[180:183], v238 offset:1024
	ds_read_b128 v[184:187], v238 offset:2048
	ds_read_b128 v[188:191], v238 offset:3072
	ds_read_b128 v[192:195], v238 offset:4096
	ds_read_b128 v[196:199], v238 offset:5120
	ds_read_b128 v[200:203], v238 offset:6144
	ds_read_b128 v[204:207], v238 offset:7168
	ds_read_b128 v[208:211], v238 offset:8192
	ds_read_b128 v[212:215], v238 offset:9216
	ds_read_b64 v[216:217], v239
	ds_read_b64 v[226:227], v239
	ds_read_b64 v[220:221], v240
	ds_read_b64 v[230:231], v240
	v_cvt_pk_bf16_f32 v32, v0, v1
	v_cvt_pk_bf16_f32 v33, v2, v3
	v_cvt_pk_bf16_f32 v34, v4, v5
	v_cvt_pk_bf16_f32 v35, v6, v7
	v_mfma_f32_16x16x32_bf16 v[48:51], v[112:115], v[120:123], 0
	v_cvt_pk_bf16_f32 v36, v8, v9
	v_cvt_pk_bf16_f32 v37, v10, v11
	v_cvt_pk_bf16_f32 v38, v12, v13
	v_cvt_pk_bf16_f32 v39, v14, v15
	v_cvt_pk_bf16_f32 v40, v16, v17
	v_cvt_pk_bf16_f32 v41, v18, v19
	v_cvt_pk_bf16_f32 v42, v20, v21
	v_cvt_pk_bf16_f32 v43, v22, v23
	v_mfma_f32_16x16x32_bf16 v[52:55], v[112:115], v[124:127], 0
	v_cvt_pk_bf16_f32 v44, v24, v25
	v_cvt_pk_bf16_f32 v45, v26, v27
	v_cvt_pk_bf16_f32 v46, v28, v29
	v_cvt_pk_bf16_f32 v47, v30, v31
	v_mfma_f32_16x16x32_bf16 v[48:51], v[80:83], v[32:35], v[48:51]
	v_mfma_f32_16x16x32_bf16 v[52:55], v[80:83], v[40:43], v[52:55]
	v_mfma_f32_16x16x32_bf16 v[56:59], v[32:35], v[88:91], 0
	v_mfma_f32_16x16x32_bf16 v[60:63], v[40:43], v[88:91], 0
	v_mfma_f32_16x16x32_bf16 v[48:51], v[84:87], v[36:39], v[48:51]
	v_mfma_f32_16x16x32_bf16 v[52:55], v[84:87], v[44:47], v[52:55]
	v_mfma_f32_16x16x32_bf16 v[56:59], v[36:39], v[92:95], v[56:59]
	v_mfma_f32_16x16x32_bf16 v[60:63], v[44:47], v[92:95], v[60:63]
	v_pk_mul_f32 v[0:1], v[0:1], v[64:65]
	v_pk_mul_f32 v[2:3], v[2:3], v[66:67]
	v_pk_mul_f32 v[4:5], v[4:5], v[68:69]
	v_pk_mul_f32 v[6:7], v[6:7], v[70:71]
	v_pk_mul_f32 v[8:9], v[8:9], v[72:73]
	v_pk_mul_f32 v[10:11], v[10:11], v[74:75]
	v_pk_mul_f32 v[12:13], v[12:13], v[76:77]
	v_pk_mul_f32 v[14:15], v[14:15], v[78:79]
	v_pk_mul_f32 v[16:17], v[16:17], v[64:65]
	v_pk_mul_f32 v[18:19], v[18:19], v[66:67]
	v_pk_mul_f32 v[20:21], v[20:21], v[68:69]
	v_pk_mul_f32 v[22:23], v[22:23], v[70:71]
	v_pk_mul_f32 v[24:25], v[24:25], v[72:73]
	v_pk_mul_f32 v[26:27], v[26:27], v[74:75]
	v_pk_mul_f32 v[28:29], v[28:29], v[76:77]
	v_pk_mul_f32 v[30:31], v[30:31], v[78:79]
	v_add_u32_e32 v241, s18, v235
	ds_read_b128 v[64:67], v241
	ds_read_b128 v[68:71], v241 offset:64
	ds_read_b128 v[72:75], v241 offset:128
	ds_read_b128 v[76:79], v241 offset:192
	s_add_i32 s17, s17, 1
	s_cmp_eq_u32 s17, 11
	s_cselect_b32 s17, 0, s17
	s_mul_i32 s18, s17, 0x3400
	v_cvt_pk_bf16_f32 v132, v48, v49
	v_cvt_pk_bf16_f32 v133, v50, v51
	v_cvt_pk_bf16_f32 v144, v52, v53
	v_cvt_pk_bf16_f32 v145, v54, v55
	s_nop 1
	v_mfma_f32_16x16x32_bf16 v[56:59], v[132:135], v[116:119], v[56:59]
	v_mfma_f32_16x16x32_bf16 v[60:63], v[144:147], v[116:119], v[60:63]
	v_mfma_f32_16x16x32_bf16 v[0:3], v[96:99], v[132:135], v[0:3]
	v_mfma_f32_16x16x32_bf16 v[4:7], v[100:103], v[132:135], v[4:7]
	v_mfma_f32_16x16x32_bf16 v[8:11], v[104:107], v[132:135], v[8:11]
	v_mfma_f32_16x16x32_bf16 v[12:15], v[108:111], v[132:135], v[12:15]
	v_mfma_f32_16x16x32_bf16 v[16:19], v[96:99], v[144:147], v[16:19]
	v_mfma_f32_16x16x32_bf16 v[20:23], v[100:103], v[144:147], v[20:23]
	v_mfma_f32_16x16x32_bf16 v[24:27], v[104:107], v[144:147], v[24:27]
	v_mfma_f32_16x16x32_bf16 v[28:31], v[108:111], v[144:147], v[28:31]
	v_cvt_pk_bf16_f32 v148, v56, v57
	v_cvt_pk_bf16_f32 v149, v58, v59
	v_cvt_pk_bf16_f32 v150, v60, v61
	v_cvt_pk_bf16_f32 v151, v62, v63
	ds_write_b64 v236, v[148:149] offset:0
	ds_write_b64 v236, v[150:151] offset:32
	s_waitcnt lgkmcnt(0)
	s_barrier
	v_add_u32_e32 v238, s18, v232
	v_add_u32_e32 v239, s18, v233
	v_add_u32_e32 v240, s18, v234
	ds_read_b128 v[80:83], v238
	ds_read_b128 v[84:87], v238 offset:1024
	ds_read_b128 v[88:91], v238 offset:2048
	ds_read_b128 v[92:95], v238 offset:3072
	ds_read_b128 v[96:99], v238 offset:4096
	ds_read_b128 v[100:103], v238 offset:5120
	ds_read_b128 v[104:107], v238 offset:6144
	ds_read_b128 v[108:111], v238 offset:7168
	ds_read_b128 v[112:115], v238 offset:8192
	ds_read_b128 v[116:119], v238 offset:9216
	ds_read_b64 v[120:121], v239
	ds_read_b64 v[134:135], v239
	ds_read_b64 v[124:125], v240
	ds_read_b64 v[146:147], v240
	v_cvt_pk_bf16_f32 v32, v0, v1
	v_cvt_pk_bf16_f32 v33, v2, v3
	v_cvt_pk_bf16_f32 v34, v4, v5
	v_cvt_pk_bf16_f32 v35, v6, v7
	v_mfma_f32_16x16x32_bf16 v[48:51], v[208:211], v[216:219], 0
	v_cvt_pk_bf16_f32 v36, v8, v9
	v_cvt_pk_bf16_f32 v37, v10, v11
	v_cvt_pk_bf16_f32 v38, v12, v13
	v_cvt_pk_bf16_f32 v39, v14, v15
	v_cvt_pk_bf16_f32 v40, v16, v17
	v_cvt_pk_bf16_f32 v41, v18, v19
	v_cvt_pk_bf16_f32 v42, v20, v21
	v_cvt_pk_bf16_f32 v43, v22, v23
	v_mfma_f32_16x16x32_bf16 v[52:55], v[208:211], v[220:223], 0
	v_cvt_pk_bf16_f32 v44, v24, v25
	v_cvt_pk_bf16_f32 v45, v26, v27
	v_cvt_pk_bf16_f32 v46, v28, v29
	v_cvt_pk_bf16_f32 v47, v30, v31
	v_mfma_f32_16x16x32_bf16 v[48:51], v[176:179], v[32:35], v[48:51]
	v_mfma_f32_16x16x32_bf16 v[52:55], v[176:179], v[40:43], v[52:55]
	v_mfma_f32_16x16x32_bf16 v[56:59], v[32:35], v[184:187], 0
	v_mfma_f32_16x16x32_bf16 v[60:63], v[40:43], v[184:187], 0
	v_mfma_f32_16x16x32_bf16 v[48:51], v[180:183], v[36:39], v[48:51]
	v_mfma_f32_16x16x32_bf16 v[52:55], v[180:183], v[44:47], v[52:55]
	v_mfma_f32_16x16x32_bf16 v[56:59], v[36:39], v[188:191], v[56:59]
	v_mfma_f32_16x16x32_bf16 v[60:63], v[44:47], v[188:191], v[60:63]
	v_pk_mul_f32 v[0:1], v[0:1], v[64:65]
	v_pk_mul_f32 v[2:3], v[2:3], v[66:67]
	v_pk_mul_f32 v[4:5], v[4:5], v[68:69]
	v_pk_mul_f32 v[6:7], v[6:7], v[70:71]
	v_pk_mul_f32 v[8:9], v[8:9], v[72:73]
	v_pk_mul_f32 v[10:11], v[10:11], v[74:75]
	v_pk_mul_f32 v[12:13], v[12:13], v[76:77]
	v_pk_mul_f32 v[14:15], v[14:15], v[78:79]
	v_pk_mul_f32 v[16:17], v[16:17], v[64:65]
	v_pk_mul_f32 v[18:19], v[18:19], v[66:67]
	v_pk_mul_f32 v[20:21], v[20:21], v[68:69]
	v_pk_mul_f32 v[22:23], v[22:23], v[70:71]
	v_pk_mul_f32 v[24:25], v[24:25], v[72:73]
	v_pk_mul_f32 v[26:27], v[26:27], v[74:75]
	v_pk_mul_f32 v[28:29], v[28:29], v[76:77]
	v_pk_mul_f32 v[30:31], v[30:31], v[78:79]
	v_add_u32_e32 v241, s18, v235
	ds_read_b128 v[64:67], v241
	ds_read_b128 v[68:71], v241 offset:64
	ds_read_b128 v[72:75], v241 offset:128
	ds_read_b128 v[76:79], v241 offset:192
	s_add_i32 s17, s17, 1
	s_cmp_eq_u32 s17, 11
	s_cselect_b32 s17, 0, s17
	s_mul_i32 s18, s17, 0x3400
	v_cvt_pk_bf16_f32 v224, v48, v49
	v_cvt_pk_bf16_f32 v225, v50, v51
	v_cvt_pk_bf16_f32 v228, v52, v53
	v_cvt_pk_bf16_f32 v229, v54, v55
	s_nop 1
	v_mfma_f32_16x16x32_bf16 v[56:59], v[224:227], v[212:215], v[56:59]
	v_mfma_f32_16x16x32_bf16 v[60:63], v[228:231], v[212:215], v[60:63]
	v_mfma_f32_16x16x32_bf16 v[0:3], v[192:195], v[224:227], v[0:3]
	v_mfma_f32_16x16x32_bf16 v[4:7], v[196:199], v[224:227], v[4:7]
	v_mfma_f32_16x16x32_bf16 v[8:11], v[200:203], v[224:227], v[8:11]
	v_mfma_f32_16x16x32_bf16 v[12:15], v[204:207], v[224:227], v[12:15]
	v_mfma_f32_16x16x32_bf16 v[16:19], v[192:195], v[228:231], v[16:19]
	v_mfma_f32_16x16x32_bf16 v[20:23], v[196:199], v[228:231], v[20:23]
	v_mfma_f32_16x16x32_bf16 v[24:27], v[200:203], v[228:231], v[24:27]
	v_mfma_f32_16x16x32_bf16 v[28:31], v[204:207], v[228:231], v[28:31]
	v_cvt_pk_bf16_f32 v148, v56, v57
	v_cvt_pk_bf16_f32 v149, v58, v59
	v_cvt_pk_bf16_f32 v150, v60, v61
	v_cvt_pk_bf16_f32 v151, v62, v63
	ds_write_b64 v236, v[148:149] offset:1024
	ds_write_b64 v236, v[150:151] offset:1056
	s_waitcnt lgkmcnt(0)
	s_barrier
	s_add_i32 s16, s16, 2
	s_cmpk_lt_u32 s16, 0x100
	s_cbranch_scc1 .Lsc_loop
	s_mov_b64 s[10:11], 0
	s_branch .LBB0_1122
.Lsc_helper:
	s_lshr_b32 s13, s12, 6
	s_sub_i32 s13, s13, 4
	v_and_b32_e32 v4, 63, v141
	v_lshrrev_b32_e32 v5, 2, v4
	v_and_b32_e32 v4, 3, v4
	v_lshlrev_b32_e32 v6, 6, v5
	v_lshl_add_u32 v6, v4, 4, v6
	s_lshl_b32 s10, s13, 11
	s_add_i32 s10, s10, 0x23c00
	v_add_u32_e32 v6, s10, v6
	v_lshlrev_b32_e32 v7, 10, v5
	v_lshl_add_u32 v7, v4, 4, v7
	s_and_b32 s10, s2, 7
	s_lshl_b32 s10, s10, 7
	s_lshl_b32 s11, s13, 6
	s_add_i32 s10, s10, s11
	v_add_u32_e32 v7, s10, v7
	s_lshr_b32 s10, s2, 3
	s_lshl_b32 s10, s10, 22
	s_add_u32 s24, s80, s10
	s_addc_u32 s25, s81, 0
	s_mov_b32 s16, 0
	s_waitcnt vmcnt(0) lgkmcnt(0)
	s_barrier
.Lsc_hloop:
	s_barrier
	ds_read_b128 v[0:3], v6
	s_waitcnt lgkmcnt(0)
	global_store_dwordx4 v7, v[0:3], s[24:25]
	s_add_u32 s24, s24, 0x4000
	s_addc_u32 s25, s25, 0
	s_barrier
	ds_read_b128 v[0:3], v6 offset:1024
	s_waitcnt lgkmcnt(0)
	global_store_dwordx4 v7, v[0:3], s[24:25]
	s_add_u32 s24, s24, 0x4000
	s_addc_u32 s25, s25, 0
	s_add_i32 s16, s16, 2
	s_cmpk_lt_u32 s16, 0x100
	s_cbranch_scc1 .Lsc_hloop
	s_branch .LBB0_1129

.LBB0_1130:
	s_add_u32 s10, s88, 0x3700
	s_addc_u32 s11, s89, 0
	s_and_b32 s18, s33, 7
	v_bfe_u32 v236, v141, 4, 1
	v_mul_u32_u24_e32 v236, 24, v236
	v_mov_b32_e32 v237, 0
	v_mbcnt_lo_u32_b32 v244, -1, 0
	v_mbcnt_hi_u32_b32 v244, -1, v244
	v_xor_b32_e32 v244, 16, v244
	v_lshlrev_b32_e32 v244, 2, v244
	s_mov_b32 s85, 0
	v_lshrrev_b32_e32 v142, 8, v141
	v_mov_b32_e32 v130, -1
	v_mov_b32_e32 v144, 0
	v_mov_b32_e32 v143, s18
	s_and_saveexec_b64 s[12:13], s[92:93]
	s_cbranch_execz .LBB0_1148
	s_waitcnt vmcnt(15)
	v_mov_b32_e32 v1, 0
	v_mov_b32_e32 v2, -1
	s_mov_b64 s[16:17], 0
	v_mov_b32_e32 v143, s18
	v_mov_b32_e32 v3, 1
	s_movk_i32 s23, 0x180
	v_mov_b32_e32 v144, 0
	s_branch .LBB0_1134

.LBB0_1163:
	s_or_b64 exec, exec, s[16:17]
	v_lshlrev_b32_e32 v207, 7, v0
	v_mov_b32_e32 v0, s74
	v_cndmask_b32_e64 v0, v92, v0, s[38:39]
	v_cndmask_b32_e64 v0, v0, v92, s[36:37]
	v_max3_f32 v92, v99, s74, v98
	v_max3_f32 v92, v92, v2, v1
	v_max3_f32 v92, v92, v124, v125
	v_max3_f32 v92, v92, v126, v127
	v_max3_f32 v92, v92, v116, v117
	v_max3_f32 v92, v92, v118, v119
	v_max3_f32 v92, v92, v108, v109
	v_max3_f32 v92, v92, v110, v111
	v_max3_f32 v92, v92, v104, v105
	v_max3_f32 v92, v92, v106, v107
	v_max3_f32 v92, v92, v100, v101
	v_max3_f32 v92, v92, v102, v103
	v_max3_f32 v92, v92, v112, v113
	v_max3_f32 v92, v92, v114, v115
	v_and_b32_e32 v205, 64, v175
	v_max3_f32 v92, v92, v120, v121
	v_xor_b32_e32 v133, 16, v175
	v_add_u32_e32 v205, 64, v205
	v_cndmask_b32_e64 v93, v203, v93, s[36:37]
	v_max3_f32 v92, v92, v122, v123
	v_cmp_lt_i32_e32 vcc, v133, v205
	v_cndmask_b32_e64 v94, v94, v203, s[44:45]
	v_cndmask_b32_e64 v95, v95, v203, s[48:49]
	v_max3_f32 v92, v92, v0, v93
	v_cndmask_b32_e32 v133, v175, v133, vcc
	v_max3_f32 v92, v92, v94, v95
	v_lshlrev_b32_e32 v133, 2, v133
	ds_bpermute_b32 v209, v133, v92
	v_lshlrev_b32_e64 v96, v129, -1
	v_or_b32_e32 v97, v207, v155
	v_and_b32_e32 v208, 7, v135
	s_waitcnt lgkmcnt(0)
	v_max_f32_e32 v209, v209, v209
	v_max_f32_e32 v92, v92, v209
	v_xor_b32_e32 v209, 32, v175
	v_cmp_lt_i32_e32 vcc, v209, v205
	s_nop 1
	v_cndmask_b32_e32 v205, v175, v209, vcc
	v_lshlrev_b32_e32 v205, 2, v205
	ds_bpermute_b32 v209, v205, v92
	s_waitcnt lgkmcnt(0)
	v_max_f32_e32 v209, v209, v209
	v_max_f32_e32 v92, v92, v209
	v_mul_f32_e32 v209, 0xbe38aa3b, v92
	v_fmamk_f32 v99, v99, 0x3e38aa3b, v209
	v_exp_f32_e32 v99, v99
	v_fmamk_f32 v98, v98, 0x3e38aa3b, v209
	v_exp_f32_e32 v98, v98
	v_fmamk_f32 v2, v2, 0x3e38aa3b, v209
	v_exp_f32_e32 v211, v2
	v_add_f32_e32 v210, 0, v99
	v_add_f32_e32 v210, v98, v210
	v_fmamk_f32 v1, v1, 0x3e38aa3b, v209
	v_add_f32_e32 v2, v211, v210
	v_exp_f32_e32 v210, v1
	v_cvt_pk_bf16_f32 v98, v99, v98
	v_fmamk_f32 v0, v0, 0x3e38aa3b, v209
	v_exp_f32_e32 v0, v0
	v_add_f32_e32 v1, v210, v2
	v_fmamk_f32 v2, v124, 0x3e38aa3b, v209
	v_exp_f32_e32 v124, v2
	v_fmamk_f32 v2, v125, 0x3e38aa3b, v209
	v_exp_f32_e32 v125, v2
	v_fmamk_f32 v2, v126, 0x3e38aa3b, v209
	v_exp_f32_e32 v126, v2
	v_fmamk_f32 v2, v127, 0x3e38aa3b, v209
	v_exp_f32_e32 v127, v2
	v_fmamk_f32 v2, v116, 0x3e38aa3b, v209
	v_exp_f32_e32 v212, v2
	v_fmamk_f32 v2, v117, 0x3e38aa3b, v209
	v_exp_f32_e32 v213, v2
	v_fmamk_f32 v2, v118, 0x3e38aa3b, v209
	v_exp_f32_e32 v118, v2
	v_fmamk_f32 v2, v119, 0x3e38aa3b, v209
	v_exp_f32_e32 v119, v2
	v_fmamk_f32 v2, v108, 0x3e38aa3b, v209
	v_exp_f32_e32 v214, v2
	v_fmamk_f32 v2, v109, 0x3e38aa3b, v209
	v_exp_f32_e32 v215, v2
	v_fmamk_f32 v2, v110, 0x3e38aa3b, v209
	v_exp_f32_e32 v216, v2
	v_fmamk_f32 v2, v111, 0x3e38aa3b, v209
	v_exp_f32_e32 v217, v2
	v_fmamk_f32 v2, v104, 0x3e38aa3b, v209
	v_exp_f32_e32 v218, v2
	v_fmamk_f32 v2, v105, 0x3e38aa3b, v209
	v_exp_f32_e32 v219, v2
	v_fmamk_f32 v2, v106, 0x3e38aa3b, v209
	v_exp_f32_e32 v220, v2
	v_fmamk_f32 v2, v107, 0x3e38aa3b, v209
	v_exp_f32_e32 v221, v2
	v_fmamk_f32 v2, v100, 0x3e38aa3b, v209
	v_exp_f32_e32 v222, v2
	v_fmamk_f32 v2, v101, 0x3e38aa3b, v209
	v_exp_f32_e32 v223, v2
	v_fmamk_f32 v2, v102, 0x3e38aa3b, v209
	v_exp_f32_e32 v224, v2
	v_fmamk_f32 v2, v103, 0x3e38aa3b, v209
	v_exp_f32_e32 v225, v2
	v_fmamk_f32 v2, v112, 0x3e38aa3b, v209
	v_add_f32_e32 v1, v124, v1
	v_exp_f32_e32 v226, v2
	v_fmamk_f32 v2, v113, 0x3e38aa3b, v209
	v_add_f32_e32 v1, v125, v1
	v_exp_f32_e32 v227, v2
	v_fmamk_f32 v2, v114, 0x3e38aa3b, v209
	v_add_f32_e32 v1, v126, v1
	v_exp_f32_e32 v228, v2
	v_fmamk_f32 v2, v115, 0x3e38aa3b, v209
	ds_read_b64_tr_b16 v[104:105], v177 offset:36864
	ds_read_b64_tr_b16 v[108:109], v177 offset:36896
	ds_read_b64_tr_b16 v[102:103], v176 offset:36864
	ds_read_b64_tr_b16 v[106:107], v176 offset:36896
	ds_read_b64_tr_b16 v[110:111], v176 offset:36928
	ds_read_b64_tr_b16 v[112:113], v177 offset:36928
	ds_read_b64_tr_b16 v[114:115], v176 offset:36960
	ds_read_b64_tr_b16 v[116:117], v177 offset:36960
	v_add_f32_e32 v1, v127, v1
	v_add_f32_e32 v1, v212, v1
	v_exp_f32_e32 v229, v2
	v_fmamk_f32 v2, v120, 0x3e38aa3b, v209
	v_add_f32_e32 v1, v213, v1
	v_exp_f32_e32 v230, v2
	v_fmamk_f32 v2, v121, 0x3e38aa3b, v209
	v_add_f32_e32 v1, v118, v1
	v_exp_f32_e32 v231, v2
	v_fmamk_f32 v2, v122, 0x3e38aa3b, v209
	v_cvt_pk_bf16_f32 v99, v211, v210
	v_cvt_pk_bf16_f32 v100, v124, v125
	v_cvt_pk_bf16_f32 v101, v126, v127
	v_add_f32_e32 v1, v119, v1
	v_exp_f32_e32 v232, v2
	v_fmamk_f32 v2, v123, 0x3e38aa3b, v209
	s_waitcnt lgkmcnt(5)
	v_mfma_f32_16x16x32_bf16 v[102:105], v[102:105], v[98:101], 0
	v_add_f32_e32 v1, v214, v1
	v_add_f32_e32 v1, v215, v1
	v_add_f32_e32 v1, v216, v1
	s_waitcnt lgkmcnt(4)
	v_mfma_f32_16x16x32_bf16 v[106:109], v[106:109], v[98:101], 0
	v_add_f32_e32 v1, v217, v1
	v_exp_f32_e32 v233, v2
	v_add_f32_e32 v1, v218, v1
	s_waitcnt lgkmcnt(2)
	v_mfma_f32_16x16x32_bf16 v[110:113], v[110:113], v[98:101], 0
	v_add_f32_e32 v1, v219, v1
	v_add_f32_e32 v1, v220, v1
	v_add_f32_e32 v1, v221, v1
	s_waitcnt lgkmcnt(0)
	v_mfma_f32_16x16x32_bf16 v[98:101], v[114:117], v[98:101], 0
	v_cvt_pk_bf16_f32 v115, v118, v119
	ds_read_b64_tr_b16 v[120:121], v179 offset:36864
	ds_read_b64_tr_b16 v[124:125], v179 offset:36896
	ds_read_b64_tr_b16 v[118:119], v178 offset:36864
	ds_read_b64_tr_b16 v[122:123], v178 offset:36896
	v_cvt_pk_bf16_f32 v114, v212, v213
	v_cvt_pk_bf16_f32 v116, v214, v215
	v_cvt_pk_bf16_f32 v117, v216, v217
	v_add_f32_e32 v1, v222, v1
	v_add_f32_e32 v1, v223, v1
	s_waitcnt lgkmcnt(1)
	v_mfma_f32_16x16x32_bf16 v[102:105], v[118:121], v[114:117], v[102:105]
	ds_read_b64_tr_b16 v[118:119], v178 offset:36928
	ds_read_b64_tr_b16 v[120:121], v179 offset:36928
	v_add_f32_e32 v1, v224, v1
	v_add_f32_e32 v1, v225, v1
	s_waitcnt lgkmcnt(0)
	v_mfma_f32_16x16x32_bf16 v[110:113], v[118:121], v[114:117], v[110:113]
	ds_read_b64_tr_b16 v[118:119], v178 offset:36960
	ds_read_b64_tr_b16 v[120:121], v179 offset:36960
	v_add_f32_e32 v1, v226, v1
	v_add_f32_e32 v1, v227, v1
	v_mfma_f32_16x16x32_bf16 v[106:109], v[122:125], v[114:117], v[106:109]
	v_add_f32_e32 v1, v228, v1
	v_add_f32_e32 v1, v229, v1
	v_add_f32_e32 v1, v230, v1
	s_waitcnt lgkmcnt(0)
	v_mfma_f32_16x16x32_bf16 v[98:101], v[118:121], v[114:117], v[98:101]
	ds_read_b64_tr_b16 v[120:121], v181 offset:36864
	ds_read_b64_tr_b16 v[124:125], v181 offset:36896
	ds_read_b64_tr_b16 v[118:119], v180 offset:36864
	ds_read_b64_tr_b16 v[122:123], v180 offset:36896
	v_cvt_pk_bf16_f32 v114, v218, v219
	v_cvt_pk_bf16_f32 v115, v220, v221
	v_cvt_pk_bf16_f32 v116, v222, v223
	v_cvt_pk_bf16_f32 v117, v224, v225
	v_fmamk_f32 v2, v93, 0x3e38aa3b, v209
	v_add_f32_e32 v1, v231, v1
	s_waitcnt lgkmcnt(1)
	v_mfma_f32_16x16x32_bf16 v[102:105], v[118:121], v[114:117], v[102:105]
	ds_read_b64_tr_b16 v[118:119], v180 offset:36928
	ds_read_b64_tr_b16 v[120:121], v181 offset:36928
	v_exp_f32_e32 v2, v2
	v_add_f32_e32 v1, v232, v1
	s_waitcnt lgkmcnt(0)
	v_mfma_f32_16x16x32_bf16 v[110:113], v[118:121], v[114:117], v[110:113]
	ds_read_b64_tr_b16 v[118:119], v180 offset:36960
	ds_read_b64_tr_b16 v[120:121], v181 offset:36960
	v_add_f32_e32 v1, v233, v1
	v_add_f32_e32 v1, v0, v1
	v_mfma_f32_16x16x32_bf16 v[106:109], v[122:125], v[114:117], v[106:109]
	v_add_f32_e32 v93, v2, v1
	v_fmamk_f32 v1, v94, 0x3e38aa3b, v209
	v_fmac_f32_e32 v209, 0x3e38aa3b, v95
	s_waitcnt lgkmcnt(0)
	v_mfma_f32_16x16x32_bf16 v[98:101], v[118:121], v[114:117], v[98:101]
	ds_read_b64_tr_b16 v[120:121], v183 offset:36864
	ds_read_b64_tr_b16 v[124:125], v183 offset:36896
	ds_read_b64_tr_b16 v[118:119], v182 offset:36864
	ds_read_b64_tr_b16 v[122:123], v182 offset:36896
	v_cvt_pk_bf16_f32 v114, v226, v227
	v_cvt_pk_bf16_f32 v115, v228, v229
	v_cvt_pk_bf16_f32 v116, v230, v231
	v_cvt_pk_bf16_f32 v117, v232, v233
	v_exp_f32_e32 v1, v1
	v_exp_f32_e32 v95, v209
	s_waitcnt lgkmcnt(1)
	v_mfma_f32_16x16x32_bf16 v[102:105], v[118:121], v[114:117], v[102:105]
	ds_read_b64_tr_b16 v[118:119], v182 offset:36928
	ds_read_b64_tr_b16 v[120:121], v183 offset:36928
	v_add_f32_e32 v93, v1, v93
	v_cvt_pk_bf16_f32 v1, v1, v95
	s_waitcnt lgkmcnt(0)
	v_mfma_f32_16x16x32_bf16 v[110:113], v[118:121], v[114:117], v[110:113]
	ds_read_b64_tr_b16 v[118:119], v182 offset:36960
	ds_read_b64_tr_b16 v[120:121], v183 offset:36960
	v_cvt_pk_bf16_f32 v0, v0, v2
	v_mov_b32_e32 v2, v3
	v_mfma_f32_16x16x32_bf16 v[106:109], v[122:125], v[114:117], v[106:109]
	v_add_f32_e32 v93, v95, v93
	ds_bpermute_b32 v94, v133, v93
	s_waitcnt lgkmcnt(0)
	v_add_f32_e32 v93, v93, v94
	v_mfma_f32_16x16x32_bf16 v[98:101], v[118:121], v[114:117], v[98:101]
	ds_read_b64_tr_b16 v[114:115], v184 offset:36864
	ds_read_b64_tr_b16 v[118:119], v184 offset:36896
	ds_bpermute_b32 v94, v205, v93
	s_waitcnt lgkmcnt(2)
	v_mov_b32_e32 v116, v114
	v_mov_b32_e32 v117, v115
	s_waitcnt lgkmcnt(1)
	v_mov_b32_e32 v120, v118
	v_mov_b32_e32 v121, v119
	v_mfma_f32_16x16x32_bf16 v[102:105], v[114:117], v[0:3], v[102:105]
	ds_read_b64_tr_b16 v[114:115], v184 offset:36928
	s_waitcnt lgkmcnt(1)
	v_add_f32_e32 v93, v93, v94
	s_waitcnt lgkmcnt(0)
	v_mov_b32_e32 v116, v114
	v_mov_b32_e32 v117, v115
	v_mfma_f32_16x16x32_bf16 v[106:109], v[118:121], v[0:3], v[106:109]
	s_nop 0
	v_mfma_f32_16x16x32_bf16 v[110:113], v[114:117], v[0:3], v[110:113]
	ds_read_b64_tr_b16 v[114:115], v184 offset:36960
	s_waitcnt lgkmcnt(0)
	v_mov_b32_e32 v116, v114
	v_mov_b32_e32 v117, v115
	s_nop 1
	v_mfma_f32_16x16x32_bf16 v[98:101], v[114:117], v[0:3], v[98:101]
	v_div_scale_f32 v0, s[16:17], v93, v93, 1.0
	v_rcp_f32_e32 v1, v0
	s_nop 0
	v_fma_f32 v2, -v0, v1, 1.0
	v_fmac_f32_e32 v1, v2, v1
	v_div_scale_f32 v2, vcc, 1.0, v93, 1.0
	v_mul_f32_e32 v94, v2, v1
	v_fma_f32 v95, -v0, v94, v2
	v_fmac_f32_e32 v94, v95, v1
	v_fma_f32 v0, -v0, v94, v2
	v_div_fmas_f32 v0, v0, v1, v94
	v_div_fixup_f32 v94, v0, v93, 1.0
	v_lshlrev_b32_e32 v0, 9, v135
	v_and_b32_e32 v0, 0x7ffff000, v0
	v_bitop3_b32 v122, v206, v0, v96 bitop3:0xdc
	v_lshl_add_u32 v2, v97, v129, v122
	v_mov_b64_e32 v[0:1], s[78:79]
	v_mad_u64_u32 v[0:1], s[16:17], v2, s26, v[0:1]
	v_lshlrev_b32_e32 v2, 10, v131
	v_lshl_add_u64 v[96:97], v[0:1], 0, v[2:3]
	v_lshlrev_b32_e32 v2, 7, v208
	v_lshl_add_u64 v[96:97], v[96:97], 0, v[2:3]
	v_mov_b32_e32 v135, v3
	v_cmp_ne_u32_e64 s[68:69], 0, v236
	v_pk_mul_f32 v[102:103], v[102:103], v[94:95] op_sel_hi:[1,0]
	v_pk_mul_f32 v[104:105], v[104:105], v[94:95] op_sel_hi:[1,0]
	v_lshl_add_u64 v[96:97], v[96:97], 0, v[134:135]
	v_pk_mul_f32 v[106:107], v[106:107], v[94:95] op_sel_hi:[1,0]
	v_pk_mul_f32 v[108:109], v[108:109], v[94:95] op_sel_hi:[1,0]
	v_pk_mul_f32 v[110:111], v[110:111], v[94:95] op_sel_hi:[1,0]
	v_pk_mul_f32 v[112:113], v[112:113], v[94:95] op_sel_hi:[1,0]
	v_pk_mul_f32 v[98:99], v[98:99], v[94:95] op_sel_hi:[1,0]
	v_pk_mul_f32 v[100:101], v[100:101], v[94:95] op_sel_hi:[1,0]
	v_cvt_pk_bf16_f32 v102, v102, v103
	v_cvt_pk_bf16_f32 v103, v104, v105
	v_cvt_pk_bf16_f32 v104, v106, v107
	v_cvt_pk_bf16_f32 v105, v108, v109
	v_cvt_pk_bf16_f32 v110, v110, v111
	v_cvt_pk_bf16_f32 v111, v112, v113
	v_cvt_pk_bf16_f32 v112, v98, v99
	v_cvt_pk_bf16_f32 v113, v100, v101
	v_lshlrev_b32_e32 v2, 2, v208
	v_lshl_or_b32 v120, v131, 5, v2
	v_cndmask_b32_e64 v240, v104, v102, s[68:69]
	v_cndmask_b32_e64 v241, v105, v103, s[68:69]
	v_cndmask_b32_e64 v242, v112, v110, s[68:69]
	v_cndmask_b32_e64 v243, v113, v111, s[68:69]
	ds_bpermute_b32 v240, v244, v240
	ds_bpermute_b32 v241, v244, v241
	ds_bpermute_b32 v242, v244, v242
	ds_bpermute_b32 v243, v244, v243
	s_waitcnt lgkmcnt(0)
	v_cndmask_b32_e64 v104, v240, v104, s[68:69]
	v_cndmask_b32_e64 v105, v241, v105, s[68:69]
	v_cndmask_b32_e64 v102, v102, v240, s[68:69]
	v_cndmask_b32_e64 v103, v103, v241, s[68:69]
	v_cndmask_b32_e64 v112, v242, v112, s[68:69]
	v_cndmask_b32_e64 v113, v243, v113, s[68:69]
	v_cndmask_b32_e64 v110, v110, v242, s[68:69]
	v_cndmask_b32_e64 v111, v111, v243, s[68:69]
	v_lshl_add_u64 v[238:239], v[96:97], 0, v[236:237]
	global_store_dwordx4 v[238:239], v[102:105], off
	global_store_dwordx4 v[238:239], v[110:113], off offset:64
	s_and_saveexec_b64 s[16:17], s[60:61]
	s_cbranch_execz .LBB0_1165
	v_cmp_gt_f32_e32 vcc, s75, v93
	v_mov_b32_e32 v121, v3
	v_lshl_add_u64 v[0:1], v[0:1], 0, v[120:121]
	v_cndmask_b32_e64 v2, 0, 32, vcc
	v_ldexp_f32 v2, v93, v2
	v_log_f32_e32 v2, v2
	s_nop 0
	v_mul_f32_e32 v93, 0x3f317217, v2
	v_fma_f32 v93, v2, s82, -v93
	v_fmac_f32_e32 v93, 0x3377d1cf, v2
	v_fmac_f32_e32 v93, 0x3f317217, v2
	v_cmp_lt_f32_e64 s[70:71], |v2|, s83
	s_nop 1
	v_cndmask_b32_e64 v2, v2, v93, s[70:71]
	v_cndmask_b32_e32 v93, 0, v204, vcc
	v_sub_f32_e32 v2, v2, v93
	v_fmac_f32_e32 v2, 0x3e000000, v92
	global_store_dword v[0:1], v2, off offset:3072

.LBB0_1167:
	s_or_b64 exec, exec, s[16:17]
	v_mov_b32_e32 v124, s74
	v_cndmask_b32_e64 v121, v84, v124, s[38:39]
	v_cndmask_b32_e64 v121, v121, v84, s[36:37]
	v_max3_f32 v84, v2, s74, v91
	v_max3_f32 v84, v84, v1, v0
	v_max3_f32 v84, v84, v116, v117
	v_max3_f32 v84, v84, v118, v119
	v_max3_f32 v84, v84, v112, v113
	v_max3_f32 v84, v84, v114, v115
	v_max3_f32 v84, v84, v108, v109
	v_max3_f32 v84, v84, v110, v111
	v_max3_f32 v84, v84, v104, v105
	v_max3_f32 v84, v84, v106, v107
	v_max3_f32 v84, v84, v100, v101
	v_max3_f32 v84, v84, v102, v103
	v_max3_f32 v84, v84, v92, v93
	v_max3_f32 v84, v84, v94, v95
	v_max3_f32 v84, v84, v96, v97
	v_cndmask_b32_e64 v85, v203, v85, s[36:37]
	v_max3_f32 v84, v84, v98, v99
	v_cndmask_b32_e64 v86, v86, v203, s[44:45]
	v_cndmask_b32_e64 v87, v87, v203, s[48:49]
	v_max3_f32 v84, v84, v121, v85
	v_max3_f32 v84, v84, v86, v87
	ds_bpermute_b32 v123, v133, v84
	v_lshlrev_b32_e32 v89, 9, v131
	v_or_b32_e32 v90, v207, v137
	v_lshlrev_b32_e32 v88, 6, v208
	s_waitcnt lgkmcnt(0)
	v_max_f32_e32 v123, v123, v123
	v_max_f32_e32 v84, v84, v123
	ds_bpermute_b32 v123, v205, v84
	s_waitcnt lgkmcnt(0)
	v_max_f32_e32 v123, v123, v123
	v_max_f32_e32 v84, v84, v123
	v_mul_f32_e32 v123, 0xbe38aa3b, v84
	v_fmamk_f32 v2, v2, 0x3e38aa3b, v123
	v_exp_f32_e32 v2, v2
	v_fmamk_f32 v91, v91, 0x3e38aa3b, v123
	v_exp_f32_e32 v91, v91
	v_fmamk_f32 v1, v1, 0x3e38aa3b, v123
	v_exp_f32_e32 v1, v1
	v_fmamk_f32 v0, v0, 0x3e38aa3b, v123
	v_exp_f32_e32 v0, v0
	v_fmamk_f32 v116, v116, 0x3e38aa3b, v123
	v_add_f32_e32 v124, 0, v2
	v_exp_f32_e32 v116, v116
	v_fmamk_f32 v117, v117, 0x3e38aa3b, v123
	v_add_f32_e32 v124, v91, v124
	v_exp_f32_e32 v117, v117
	v_fmamk_f32 v118, v118, 0x3e38aa3b, v123
	v_add_f32_e32 v124, v1, v124
	v_exp_f32_e32 v118, v118
	v_fmamk_f32 v119, v119, 0x3e38aa3b, v123
	v_add_f32_e32 v124, v0, v124
	v_exp_f32_e32 v119, v119
	v_fmamk_f32 v112, v112, 0x3e38aa3b, v123
	v_add_f32_e32 v124, v116, v124
	v_exp_f32_e32 v112, v112
	v_fmamk_f32 v113, v113, 0x3e38aa3b, v123
	v_add_f32_e32 v124, v117, v124
	v_exp_f32_e32 v113, v113
	v_fmamk_f32 v114, v114, 0x3e38aa3b, v123
	v_add_f32_e32 v124, v118, v124
	v_exp_f32_e32 v114, v114
	v_fmamk_f32 v115, v115, 0x3e38aa3b, v123
	v_add_f32_e32 v124, v119, v124
	v_exp_f32_e32 v115, v115
	v_fmamk_f32 v108, v108, 0x3e38aa3b, v123
	v_add_f32_e32 v124, v112, v124
	v_exp_f32_e32 v125, v108
	v_add_f32_e32 v124, v113, v124
	v_add_f32_e32 v124, v114, v124
	v_add_f32_e32 v124, v115, v124
	v_fmamk_f32 v109, v109, 0x3e38aa3b, v123
	v_add_f32_e32 v108, v125, v124
	v_exp_f32_e32 v124, v109
	v_fmamk_f32 v109, v110, 0x3e38aa3b, v123
	v_exp_f32_e32 v126, v109
	v_fmamk_f32 v109, v111, 0x3e38aa3b, v123
	v_exp_f32_e32 v127, v109
	v_fmamk_f32 v104, v104, 0x3e38aa3b, v123
	v_exp_f32_e32 v131, v104
	v_fmamk_f32 v105, v105, 0x3e38aa3b, v123
	v_add_f32_e32 v108, v124, v108
	v_exp_f32_e32 v135, v105
	v_fmamk_f32 v105, v106, 0x3e38aa3b, v123
	v_add_f32_e32 v108, v126, v108
	v_exp_f32_e32 v206, v105
	v_fmamk_f32 v105, v107, 0x3e38aa3b, v123
	v_add_f32_e32 v108, v127, v108
	v_exp_f32_e32 v207, v105
	v_fmamk_f32 v100, v100, 0x3e38aa3b, v123
	v_add_f32_e32 v104, v131, v108
	v_exp_f32_e32 v208, v100
	v_fmamk_f32 v101, v101, 0x3e38aa3b, v123
	v_add_f32_e32 v104, v135, v104
	v_exp_f32_e32 v209, v101
	v_fmamk_f32 v101, v102, 0x3e38aa3b, v123
	v_add_f32_e32 v104, v206, v104
	v_exp_f32_e32 v210, v101
	v_fmamk_f32 v101, v103, 0x3e38aa3b, v123
	v_add_f32_e32 v104, v207, v104
	v_exp_f32_e32 v211, v101
	v_fmamk_f32 v92, v92, 0x3e38aa3b, v123
	v_add_f32_e32 v100, v208, v104
	v_exp_f32_e32 v212, v92
	v_fmamk_f32 v93, v93, 0x3e38aa3b, v123
	v_add_f32_e32 v100, v209, v100
	v_exp_f32_e32 v213, v93
	v_fmamk_f32 v93, v94, 0x3e38aa3b, v123
	v_add_f32_e32 v100, v210, v100
	v_exp_f32_e32 v214, v93
	v_fmamk_f32 v93, v95, 0x3e38aa3b, v123
	v_add_f32_e32 v100, v211, v100
	v_exp_f32_e32 v215, v93
	v_fmamk_f32 v93, v96, 0x3e38aa3b, v123
	v_add_f32_e32 v92, v212, v100
	v_exp_f32_e32 v216, v93
	v_fmamk_f32 v93, v97, 0x3e38aa3b, v123
	v_add_f32_e32 v92, v213, v92
	v_exp_f32_e32 v217, v93
	v_fmamk_f32 v93, v98, 0x3e38aa3b, v123
	v_add_f32_e32 v92, v214, v92
	v_exp_f32_e32 v218, v93
	v_fmamk_f32 v93, v99, 0x3e38aa3b, v123
	v_add_f32_e32 v92, v215, v92
	v_exp_f32_e32 v219, v93
	v_fmamk_f32 v93, v121, 0x3e38aa3b, v123
	v_add_f32_e32 v92, v216, v92
	v_exp_f32_e32 v121, v93
	v_fmamk_f32 v85, v85, 0x3e38aa3b, v123
	v_add_f32_e32 v92, v217, v92
	v_exp_f32_e32 v220, v85
	ds_read_b64_tr_b16 v[98:99], v195 offset:36864
	ds_read_b64_tr_b16 v[102:103], v195 offset:36896
	ds_read_b64_tr_b16 v[96:97], v194 offset:36864
	ds_read_b64_tr_b16 v[100:101], v194 offset:36896
	ds_read_b64_tr_b16 v[104:105], v194 offset:36928
	ds_read_b64_tr_b16 v[106:107], v195 offset:36928
	ds_read_b64_tr_b16 v[108:109], v194 offset:36960
	ds_read_b64_tr_b16 v[110:111], v195 offset:36960
	v_add_f32_e32 v92, v218, v92
	v_add_f32_e32 v92, v219, v92
	v_add_f32_e32 v92, v121, v92
	v_add_f32_e32 v85, v220, v92
	v_cvt_pk_bf16_f32 v92, v2, v91
	v_cvt_pk_bf16_f32 v93, v1, v0
	v_cvt_pk_bf16_f32 v94, v116, v117
	v_cvt_pk_bf16_f32 v95, v118, v119
	v_fmamk_f32 v86, v86, 0x3e38aa3b, v123
	v_fmac_f32_e32 v123, 0x3e38aa3b, v87
	s_waitcnt lgkmcnt(5)
	v_mfma_f32_16x16x32_bf16 v[96:99], v[96:99], v[92:95], 0
	v_exp_f32_e32 v221, v86
	v_exp_f32_e32 v87, v123
	v_cvt_pk_bf16_f32 v0, v121, v220
	s_waitcnt lgkmcnt(4)
	v_mfma_f32_16x16x32_bf16 v[100:103], v[100:103], v[92:95], 0
	v_mov_b32_e32 v2, v3
	v_cvt_pk_bf16_f32 v1, v221, v87
	v_add_f32_e32 v85, v221, v85
	s_waitcnt lgkmcnt(2)
	v_mfma_f32_16x16x32_bf16 v[104:107], v[104:107], v[92:95], 0
	v_add_f32_e32 v85, v87, v85
	ds_bpermute_b32 v86, v133, v85
	s_waitcnt lgkmcnt(0)
	v_add_f32_e32 v85, v85, v86
	v_mfma_f32_16x16x32_bf16 v[92:95], v[108:111], v[92:95], 0
	v_cvt_pk_bf16_f32 v108, v112, v113
	v_cvt_pk_bf16_f32 v109, v114, v115
	ds_read_b64_tr_b16 v[114:115], v197 offset:36864
	ds_read_b64_tr_b16 v[118:119], v197 offset:36896
	ds_read_b64_tr_b16 v[112:113], v196 offset:36864
	ds_read_b64_tr_b16 v[116:117], v196 offset:36896
	v_cvt_pk_bf16_f32 v110, v125, v124
	v_cvt_pk_bf16_f32 v111, v126, v127
	ds_bpermute_b32 v86, v205, v85
	s_waitcnt lgkmcnt(0)
	v_add_f32_e32 v85, v85, v86
	v_mfma_f32_16x16x32_bf16 v[96:99], v[112:115], v[108:111], v[96:99]
	ds_read_b64_tr_b16 v[112:113], v196 offset:36928
	ds_read_b64_tr_b16 v[114:115], v197 offset:36928
	s_waitcnt lgkmcnt(0)
	v_mfma_f32_16x16x32_bf16 v[104:107], v[112:115], v[108:111], v[104:107]
	ds_read_b64_tr_b16 v[112:113], v196 offset:36960
	ds_read_b64_tr_b16 v[114:115], v197 offset:36960
	v_mfma_f32_16x16x32_bf16 v[100:103], v[116:119], v[108:111], v[100:103]
	s_waitcnt lgkmcnt(0)
	v_mfma_f32_16x16x32_bf16 v[92:95], v[112:115], v[108:111], v[92:95]
	ds_read_b64_tr_b16 v[114:115], v199 offset:36864
	ds_read_b64_tr_b16 v[118:119], v199 offset:36896
	ds_read_b64_tr_b16 v[112:113], v198 offset:36864
	ds_read_b64_tr_b16 v[116:117], v198 offset:36896
	v_cvt_pk_bf16_f32 v108, v131, v135
	v_cvt_pk_bf16_f32 v109, v206, v207
	v_cvt_pk_bf16_f32 v110, v208, v209
	v_cvt_pk_bf16_f32 v111, v210, v211
	v_mov_b32_e32 v135, v3
	s_waitcnt lgkmcnt(1)
	v_mfma_f32_16x16x32_bf16 v[96:99], v[112:115], v[108:111], v[96:99]
	ds_read_b64_tr_b16 v[112:113], v198 offset:36928
	ds_read_b64_tr_b16 v[114:115], v199 offset:36928
	s_waitcnt lgkmcnt(0)
	v_mfma_f32_16x16x32_bf16 v[104:107], v[112:115], v[108:111], v[104:107]
	ds_read_b64_tr_b16 v[112:113], v198 offset:36960
	ds_read_b64_tr_b16 v[114:115], v199 offset:36960
	v_mfma_f32_16x16x32_bf16 v[100:103], v[116:119], v[108:111], v[100:103]
	s_waitcnt lgkmcnt(0)
	v_mfma_f32_16x16x32_bf16 v[92:95], v[112:115], v[108:111], v[92:95]
	ds_read_b64_tr_b16 v[114:115], v201 offset:36864
	ds_read_b64_tr_b16 v[118:119], v201 offset:36896
	ds_read_b64_tr_b16 v[112:113], v200 offset:36864
	ds_read_b64_tr_b16 v[116:117], v200 offset:36896
	v_cvt_pk_bf16_f32 v108, v212, v213
	v_cvt_pk_bf16_f32 v109, v214, v215
	v_cvt_pk_bf16_f32 v110, v216, v217
	v_cvt_pk_bf16_f32 v111, v218, v219
	s_waitcnt lgkmcnt(1)
	s_nop 0
	v_mfma_f32_16x16x32_bf16 v[96:99], v[112:115], v[108:111], v[96:99]
	ds_read_b64_tr_b16 v[112:113], v200 offset:36928
	ds_read_b64_tr_b16 v[114:115], v201 offset:36928
	s_waitcnt lgkmcnt(0)
	v_mfma_f32_16x16x32_bf16 v[104:107], v[112:115], v[108:111], v[104:107]
	ds_read_b64_tr_b16 v[112:113], v200 offset:36960
	ds_read_b64_tr_b16 v[114:115], v201 offset:36960
	v_mfma_f32_16x16x32_bf16 v[100:103], v[116:119], v[108:111], v[100:103]
	s_waitcnt lgkmcnt(0)
	v_mfma_f32_16x16x32_bf16 v[92:95], v[112:115], v[108:111], v[92:95]
	ds_read_b64_tr_b16 v[108:109], v202 offset:36864
	ds_read_b64_tr_b16 v[112:113], v202 offset:36896
	s_waitcnt lgkmcnt(1)
	v_mov_b32_e32 v110, v108
	v_mov_b32_e32 v111, v109
	s_waitcnt lgkmcnt(0)
	v_mov_b32_e32 v114, v112
	v_mov_b32_e32 v115, v113
	v_mfma_f32_16x16x32_bf16 v[96:99], v[108:111], v[0:3], v[96:99]
	ds_read_b64_tr_b16 v[108:109], v202 offset:36928
	s_waitcnt lgkmcnt(0)
	v_mov_b32_e32 v110, v108
	v_mov_b32_e32 v111, v109
	v_mfma_f32_16x16x32_bf16 v[100:103], v[112:115], v[0:3], v[100:103]
	s_nop 0
	v_mfma_f32_16x16x32_bf16 v[104:107], v[108:111], v[0:3], v[104:107]
	ds_read_b64_tr_b16 v[108:109], v202 offset:36960
	s_waitcnt lgkmcnt(0)
	v_mov_b32_e32 v110, v108
	v_mov_b32_e32 v111, v109
	s_nop 1
	v_mfma_f32_16x16x32_bf16 v[92:95], v[108:111], v[0:3], v[92:95]
	v_div_scale_f32 v0, s[16:17], v85, v85, 1.0
	v_rcp_f32_e32 v1, v0
	s_nop 0
	v_fma_f32 v2, -v0, v1, 1.0
	v_fmac_f32_e32 v1, v2, v1
	v_div_scale_f32 v2, vcc, 1.0, v85, 1.0
	v_mul_f32_e32 v86, v2, v1
	v_fma_f32 v87, -v0, v86, v2
	v_fmac_f32_e32 v86, v87, v1
	v_fma_f32 v0, -v0, v86, v2
	v_div_fmas_f32 v0, v0, v1, v86
	v_div_fixup_f32 v86, v0, v85, 1.0
	v_lshl_add_u32 v2, v90, v129, v122
	v_mov_b64_e32 v[0:1], s[78:79]
	v_mad_u64_u32 v[0:1], s[16:17], v2, s26, v[0:1]
	v_lshlrev_b32_e32 v2, 1, v89
	v_lshl_add_u64 v[90:91], v[0:1], 0, v[2:3]
	v_lshlrev_b32_e32 v2, 1, v88
	v_lshl_add_u64 v[88:89], v[90:91], 0, v[2:3]
	v_cmp_ne_u32_e64 s[68:69], 0, v236
	v_pk_mul_f32 v[96:97], v[96:97], v[86:87] op_sel_hi:[1,0]
	v_pk_mul_f32 v[98:99], v[98:99], v[86:87] op_sel_hi:[1,0]
	v_lshl_add_u64 v[88:89], v[88:89], 0, v[134:135]
	v_pk_mul_f32 v[100:101], v[100:101], v[86:87] op_sel_hi:[1,0]
	v_pk_mul_f32 v[102:103], v[102:103], v[86:87] op_sel_hi:[1,0]
	v_pk_mul_f32 v[104:105], v[104:105], v[86:87] op_sel_hi:[1,0]
	v_pk_mul_f32 v[106:107], v[106:107], v[86:87] op_sel_hi:[1,0]
	v_pk_mul_f32 v[92:93], v[92:93], v[86:87] op_sel_hi:[1,0]
	v_pk_mul_f32 v[94:95], v[94:95], v[86:87] op_sel_hi:[1,0]
	v_cvt_pk_bf16_f32 v96, v96, v97
	v_cvt_pk_bf16_f32 v97, v98, v99
	v_cvt_pk_bf16_f32 v98, v100, v101
	v_cvt_pk_bf16_f32 v99, v102, v103
	v_cvt_pk_bf16_f32 v104, v104, v105
	v_cvt_pk_bf16_f32 v105, v106, v107
	v_cvt_pk_bf16_f32 v106, v92, v93
	v_cvt_pk_bf16_f32 v107, v94, v95
	v_cndmask_b32_e64 v240, v98, v96, s[68:69]
	v_cndmask_b32_e64 v241, v99, v97, s[68:69]
	v_cndmask_b32_e64 v242, v106, v104, s[68:69]
	v_cndmask_b32_e64 v243, v107, v105, s[68:69]
	ds_bpermute_b32 v240, v244, v240
	ds_bpermute_b32 v241, v244, v241
	ds_bpermute_b32 v242, v244, v242
	ds_bpermute_b32 v243, v244, v243
	s_waitcnt lgkmcnt(0)
	v_cndmask_b32_e64 v98, v240, v98, s[68:69]
	v_cndmask_b32_e64 v99, v241, v99, s[68:69]
	v_cndmask_b32_e64 v96, v96, v240, s[68:69]
	v_cndmask_b32_e64 v97, v97, v241, s[68:69]
	v_cndmask_b32_e64 v106, v242, v106, s[68:69]
	v_cndmask_b32_e64 v107, v243, v107, s[68:69]
	v_cndmask_b32_e64 v104, v104, v242, s[68:69]
	v_cndmask_b32_e64 v105, v105, v243, s[68:69]
	v_lshl_add_u64 v[238:239], v[88:89], 0, v[236:237]
	global_store_dwordx4 v[238:239], v[96:99], off
	global_store_dwordx4 v[238:239], v[104:107], off offset:64
	s_and_saveexec_b64 s[16:17], s[60:61]
	s_cbranch_execz .LBB0_1150
	v_cmp_gt_f32_e32 vcc, s75, v85
	v_mov_b32_e32 v121, v3
	v_lshl_add_u64 v[0:1], v[0:1], 0, v[120:121]
	v_cndmask_b32_e64 v2, 0, 32, vcc
	v_ldexp_f32 v2, v85, v2
	v_log_f32_e32 v2, v2
	s_nop 0
	v_mul_f32_e32 v85, 0x3f317217, v2
	v_fma_f32 v85, v2, s82, -v85
	v_fmac_f32_e32 v85, 0x3377d1cf, v2
	v_fmac_f32_e32 v85, 0x3f317217, v2
	v_cmp_lt_f32_e64 s[66:67], |v2|, s83
	s_nop 1
	v_cndmask_b32_e64 v2, v2, v85, s[66:67]
	v_cndmask_b32_e32 v85, 0, v204, vcc
	v_sub_f32_e32 v2, v2, v85
	v_fmac_f32_e32 v2, 0x3e000000, v84
	global_store_dword v[0:1], v2, off offset:3072
	s_branch .LBB0_1150
